# grid barrier: in-loop syncs use XSUB arrival + direct TOP poll by all WGs (drops TOPGEN/XGEN hops)
# speedup vs baseline: 1.0151x; 1.0016x over previous
; #define LAS __attribute__((address_space(3)))
; __device__ __forceinline__ unsigned xb_ld(unsigned* p)              { return __hip_atomic_load(p, __ATOMIC_RELAXED, __HIP_MEMORY_SCOPE_AGENT); }
; __device__ __forceinline__ unsigned xb_add(unsigned* p, unsigned v) { return __hip_atomic_fetch_add(p, v, __ATOMIC_RELAXED, __HIP_MEMORY_SCOPE_AGENT); }
; __device__ __forceinline__ unsigned xb_xcc_id() { return (unsigned)__builtin_amdgcn_s_getreg((3 << 11) | 20) & 0xFu; }
; #define XB_SPIN(cond, bar) do { unsigned _sp = 0; while (cond) { __builtin_amdgcn_s_sleep(1); \
;     if ((++_sp & 255u) == 0u) { if (xb_ld(&(bar)[XB_TMO])) break; if (_sp > XB_SPIN_CAP) { atomicAdd(&(bar)[XB_TMO], 1u); break; } } } } while (0)
; __device__ __forceinline__ void xcd_barrier(unsigned* bar, volatile LAS unsigned* st) {
;     asm volatile("s_waitcnt vmcnt(0)" ::: "memory");
;     __syncthreads();
;     if (threadIdx.x == 0) {
;         __builtin_amdgcn_s_waitcnt(0);
;         const unsigned x = xb_xcc_id();
;         unsigned nloc = st[0], nx = st[1];
;         if (nloc == 0u) { xcd_barrier_complete(bar, x, nloc, nx); st[0] = nloc; st[1] = nx; }
;         const unsigned old = xb_add(&bar[XB_XSUB(x)], 1u);
;         const unsigned gen = old / nloc;
;         if (old + 1u == (gen + 1u) * nloc) {
;             __builtin_amdgcn_fence(__ATOMIC_RELEASE, "agent");
;             asm volatile("s_waitcnt vmcnt(0)" ::: "memory");
;             const unsigned og = xb_add(&bar[XB_TOP], 1u);
;             const unsigned tg = og / nx;
;             if (og + 1u == (tg + 1u) * nx) xb_add(&bar[XB_TOPGEN], 1u);
;             else XB_SPIN(xb_ld(&bar[XB_TOPGEN]) == tg, bar);
;             __builtin_amdgcn_fence(__ATOMIC_ACQUIRE, "agent");
;             xb_add(&bar[XB_XGEN(x)], 1u);
;             asm volatile("s_waitcnt vmcnt(0)" ::: "memory");
;         } else {
;             XB_SPIN(xb_ld(&bar[XB_XGEN(x)]) == gen, bar);
;             __builtin_amdgcn_fence(__ATOMIC_ACQUIRE, "agent");
;             asm volatile("s_waitcnt vmcnt(0)" ::: "memory");
;         }
;     }
;     __syncthreads();
; }
.LBB0_407:
	s_mov_b64 s[4:5], s[86:87]
	s_waitcnt vmcnt(0)
	s_waitcnt vmcnt(0)
	s_barrier
	s_and_saveexec_b64 s[6:7], s[88:89]
	s_mov_b32 s23, 0x16400000
	s_cbranch_execz .LBB0_459
	v_readlane_b32 s0, v255, 22
	s_load_dwordx2 s[8:9], s[4:5], 0x98
	v_readlane_b32 s1, v255, 23
	s_getreg_b32 s10, hwreg(HW_REG_XCC_ID, 0, 4)
	v_mov_b32_e32 v0, s0
	v_mov_b32_e32 v1, s1
	ds_read_b32 v2, v0
	ds_read_b32 v3, v1
	s_and_b32 s10, s10, 15
	s_lshl_b32 s10, s10, 8
	v_mov_b32_e32 v0, 0x1400
	v_mov_b32_e32 v1, 1
	s_waitcnt vmcnt(0) lgkmcnt(0)
	s_add_u32 s10, s8, s10
	s_addc_u32 s11, s9, 0
	global_atomic_add v4, v0, v1, s[10:11] sc0
	v_cvt_f32_u32_e32 v5, v2
	v_mov_b32_e32 v0, 0x3400
	v_rcp_f32_e32 v5, v5
	s_waitcnt vmcnt(0)
	v_cvt_f32_u32_e32 v6, v4
	v_add_u32_e32 v4, 1, v4
	v_add_f32_e32 v6, 0.5, v6
	v_mul_f32_e32 v6, v6, v5
	v_cvt_u32_f32_e32 v6, v6
	v_add_u32_e32 v6, 1, v6
	v_mul_lo_u32 v7, v6, v2
	v_mul_lo_u32 v6, v6, v3
	v_cmp_eq_u32_e32 vcc, v4, v7
	s_cbranch_vccz .Lxb_poll_0
	buffer_wbl2 sc1
	s_waitcnt vmcnt(0)
	global_atomic_add v0, v1, s[8:9]
.Lxb_poll_0:
	s_mov_b32 s0, 0
.Lxb_spin_0:
	global_load_dword v4, v0, s[8:9] sc1
	s_waitcnt vmcnt(0)
	v_sub_u32_e32 v4, v4, v6
	v_cmp_gt_i32_e32 vcc, 0, v4
	s_cbranch_vccz .Lxb_done_0
	s_sleep 1
	s_add_u32 s0, s0, 1
	s_cmp_lt_u32 s0, 0x10000
	s_cbranch_scc1 .Lxb_spin_0
.Lxb_done_0:
	buffer_inv sc1
	s_waitcnt vmcnt(0)

; #define LAS __attribute__((address_space(3)))
; __device__ __forceinline__ unsigned xb_add(unsigned* p, unsigned v) { return __hip_atomic_fetch_add(p, v, __ATOMIC_RELAXED, __HIP_MEMORY_SCOPE_AGENT); }
; __device__ __forceinline__ unsigned xb_xcc_id() { return (unsigned)__builtin_amdgcn_s_getreg((3 << 11) | 20) & 0xFu; }
; __device__ __forceinline__ void xcd_barrier(unsigned* bar, volatile LAS unsigned* st) {
;     asm volatile("s_waitcnt vmcnt(0)" ::: "memory");
;     __syncthreads();
;     if (threadIdx.x == 0) {
;         __builtin_amdgcn_s_waitcnt(0);
;         const unsigned x = xb_xcc_id();
;         unsigned nloc = st[0], nx = st[1];
;         if (nloc == 0u) { xcd_barrier_complete(bar, x, nloc, nx); st[0] = nloc; st[1] = nx; }
;         const unsigned old = xb_add(&bar[XB_XSUB(x)], 1u);
;         const unsigned gen = old / nloc;
;         if (old + 1u == (gen + 1u) * nloc) {
;             __builtin_amdgcn_fence(__ATOMIC_RELEASE, "agent");
;             asm volatile("s_waitcnt vmcnt(0)" ::: "memory");
;             const unsigned og = xb_add(&bar[XB_TOP], 1u);
;             const unsigned tg = og / nx;
;             if (og + 1u == (tg + 1u) * nx) xb_add(&bar[XB_TOPGEN], 1u);
.LBB0_467:
	s_mov_b64 s[4:5], s[86:87]
	s_waitcnt vmcnt(0)
	s_barrier
	s_and_saveexec_b64 s[6:7], s[88:89]
	s_cbranch_execz .LBB0_519
	v_readlane_b32 s0, v255, 22
	s_load_dwordx2 s[8:9], s[4:5], 0x98
	v_readlane_b32 s1, v255, 23
	s_getreg_b32 s10, hwreg(HW_REG_XCC_ID, 0, 4)
	v_mov_b32_e32 v0, s0
	v_mov_b32_e32 v1, s1
	ds_read_b32 v2, v0
	ds_read_b32 v3, v1
	s_and_b32 s10, s10, 15
	s_lshl_b32 s10, s10, 8
	v_mov_b32_e32 v0, 0x1400
	v_mov_b32_e32 v1, 1
	s_waitcnt vmcnt(0) lgkmcnt(0)
	s_add_u32 s10, s8, s10
	s_addc_u32 s11, s9, 0
	global_atomic_add v4, v0, v1, s[10:11] sc0
	v_cvt_f32_u32_e32 v5, v2
	v_mov_b32_e32 v0, 0x3400
	v_rcp_f32_e32 v5, v5
	s_waitcnt vmcnt(0)
	v_cvt_f32_u32_e32 v6, v4
	v_add_u32_e32 v4, 1, v4
	v_add_f32_e32 v6, 0.5, v6
	v_mul_f32_e32 v6, v6, v5
	v_cvt_u32_f32_e32 v6, v6
	v_add_u32_e32 v6, 1, v6
	v_mul_lo_u32 v7, v6, v2
	v_mul_lo_u32 v6, v6, v3
	v_cmp_eq_u32_e32 vcc, v4, v7
	s_cbranch_vccz .Lxb_poll_1
	buffer_wbl2 sc1
	s_waitcnt vmcnt(0)
	global_atomic_add v0, v1, s[8:9]

; #define LAS __attribute__((address_space(3)))
; __device__ __forceinline__ unsigned xb_add(unsigned* p, unsigned v) { return __hip_atomic_fetch_add(p, v, __ATOMIC_RELAXED, __HIP_MEMORY_SCOPE_AGENT); }
; __device__ __forceinline__ unsigned xb_xcc_id() { return (unsigned)__builtin_amdgcn_s_getreg((3 << 11) | 20) & 0xFu; }
; __device__ __forceinline__ void xcd_barrier(unsigned* bar, volatile LAS unsigned* st) {
;     asm volatile("s_waitcnt vmcnt(0)" ::: "memory");
;     __syncthreads();
;     if (threadIdx.x == 0) {
;         __builtin_amdgcn_s_waitcnt(0);
;         const unsigned x = xb_xcc_id();
;         unsigned nloc = st[0], nx = st[1];
;         if (nloc == 0u) { xcd_barrier_complete(bar, x, nloc, nx); st[0] = nloc; st[1] = nx; }
;         const unsigned old = xb_add(&bar[XB_XSUB(x)], 1u);
;         const unsigned gen = old / nloc;
;         if (old + 1u == (gen + 1u) * nloc) {
;             __builtin_amdgcn_fence(__ATOMIC_RELEASE, "agent");
;             asm volatile("s_waitcnt vmcnt(0)" ::: "memory");
;             const unsigned og = xb_add(&bar[XB_TOP], 1u);
;             const unsigned tg = og / nx;
;             if (og + 1u == (tg + 1u) * nx) xb_add(&bar[XB_TOPGEN], 1u);
.LBB0_743:
	s_mov_b64 s[4:5], s[86:87]
	s_waitcnt vmcnt(0)
	s_waitcnt vmcnt(0)
	s_barrier
	s_and_saveexec_b64 s[6:7], s[88:89]
	s_cbranch_execz .LBB0_795
	v_readlane_b32 s0, v255, 22
	s_load_dwordx2 s[8:9], s[4:5], 0x98
	v_readlane_b32 s1, v255, 23
	s_getreg_b32 s10, hwreg(HW_REG_XCC_ID, 0, 4)
	v_mov_b32_e32 v0, s0
	v_mov_b32_e32 v1, s1
	ds_read_b32 v2, v0
	ds_read_b32 v3, v1
	s_and_b32 s10, s10, 15
	s_lshl_b32 s10, s10, 8
	v_mov_b32_e32 v0, 0x1400
	v_mov_b32_e32 v1, 1
	s_waitcnt vmcnt(0) lgkmcnt(0)
	s_add_u32 s10, s8, s10
	s_addc_u32 s11, s9, 0
	global_atomic_add v4, v0, v1, s[10:11] sc0
	v_cvt_f32_u32_e32 v5, v2
	v_mov_b32_e32 v0, 0x3400
	v_rcp_f32_e32 v5, v5
	s_waitcnt vmcnt(0)
	v_cvt_f32_u32_e32 v6, v4
	v_add_u32_e32 v4, 1, v4
	v_add_f32_e32 v6, 0.5, v6
	v_mul_f32_e32 v6, v6, v5
	v_cvt_u32_f32_e32 v6, v6
	v_add_u32_e32 v6, 1, v6
	v_mul_lo_u32 v7, v6, v2
	v_mul_lo_u32 v6, v6, v3
	v_cmp_eq_u32_e32 vcc, v4, v7
	s_cbranch_vccz .Lxb_poll_2
	buffer_wbl2 sc1
	s_waitcnt vmcnt(0)
	global_atomic_add v0, v1, s[8:9]

; #define LAS __attribute__((address_space(3)))
; __device__ __forceinline__ unsigned xb_add(unsigned* p, unsigned v) { return __hip_atomic_fetch_add(p, v, __ATOMIC_RELAXED, __HIP_MEMORY_SCOPE_AGENT); }
; __device__ __forceinline__ unsigned xb_xcc_id() { return (unsigned)__builtin_amdgcn_s_getreg((3 << 11) | 20) & 0xFu; }
; __device__ __forceinline__ void xcd_barrier(unsigned* bar, volatile LAS unsigned* st) {
;     asm volatile("s_waitcnt vmcnt(0)" ::: "memory");
;     __syncthreads();
;     if (threadIdx.x == 0) {
;         __builtin_amdgcn_s_waitcnt(0);
;         const unsigned x = xb_xcc_id();
;         unsigned nloc = st[0], nx = st[1];
;         if (nloc == 0u) { xcd_barrier_complete(bar, x, nloc, nx); st[0] = nloc; st[1] = nx; }
;         const unsigned old = xb_add(&bar[XB_XSUB(x)], 1u);
;         const unsigned gen = old / nloc;
;         if (old + 1u == (gen + 1u) * nloc) {
;             __builtin_amdgcn_fence(__ATOMIC_RELEASE, "agent");
;             asm volatile("s_waitcnt vmcnt(0)" ::: "memory");
;             const unsigned og = xb_add(&bar[XB_TOP], 1u);
;             const unsigned tg = og / nx;
;             if (og + 1u == (tg + 1u) * nx) xb_add(&bar[XB_TOPGEN], 1u);
.LBB0_863:
	s_setprio 0
	s_mov_b64 s[4:5], s[86:87]
	s_waitcnt vmcnt(0)
	s_waitcnt lgkmcnt(0)
	s_barrier
	s_and_saveexec_b64 s[6:7], s[88:89]
	v_readlane_b32 s58, v255, 32
	v_readlane_b32 s34, v255, 26
	v_readlane_b32 s59, v255, 33
	s_mov_b32 s23, 0x16400000
	v_readlane_b32 s35, v255, 27
	s_cbranch_execz .LBB0_915
	v_readlane_b32 s0, v255, 22
	s_load_dwordx2 s[8:9], s[4:5], 0x98
	v_readlane_b32 s1, v255, 23
	s_getreg_b32 s10, hwreg(HW_REG_XCC_ID, 0, 4)
	v_mov_b32_e32 v0, s0
	v_mov_b32_e32 v1, s1
	ds_read_b32 v2, v0
	ds_read_b32 v3, v1
	s_and_b32 s10, s10, 15
	s_lshl_b32 s10, s10, 8
	v_mov_b32_e32 v0, 0x1400
	v_mov_b32_e32 v1, 1
	s_waitcnt vmcnt(0) lgkmcnt(0)
	s_add_u32 s10, s8, s10
	s_addc_u32 s11, s9, 0
	global_atomic_add v4, v0, v1, s[10:11] sc0
	v_cvt_f32_u32_e32 v5, v2
	v_mov_b32_e32 v0, 0x3400
	v_rcp_f32_e32 v5, v5
	s_waitcnt vmcnt(0)
	v_cvt_f32_u32_e32 v6, v4
	v_add_u32_e32 v4, 1, v4
	v_add_f32_e32 v6, 0.5, v6
	v_mul_f32_e32 v6, v6, v5
	v_cvt_u32_f32_e32 v6, v6
	v_add_u32_e32 v6, 1, v6
	v_mul_lo_u32 v7, v6, v2
	v_mul_lo_u32 v6, v6, v3
	v_cmp_eq_u32_e32 vcc, v4, v7
	s_cbranch_vccz .Lxb_poll_3
	buffer_wbl2 sc1
	s_waitcnt vmcnt(0)
	global_atomic_add v0, v1, s[8:9]

; #define LAS __attribute__((address_space(3)))
; __device__ __forceinline__ unsigned xb_add(unsigned* p, unsigned v) { return __hip_atomic_fetch_add(p, v, __ATOMIC_RELAXED, __HIP_MEMORY_SCOPE_AGENT); }
; __device__ __forceinline__ unsigned xb_xcc_id() { return (unsigned)__builtin_amdgcn_s_getreg((3 << 11) | 20) & 0xFu; }
; __device__ __forceinline__ void xcd_barrier(unsigned* bar, volatile LAS unsigned* st) {
;     asm volatile("s_waitcnt vmcnt(0)" ::: "memory");
;     __syncthreads();
;     if (threadIdx.x == 0) {
;         __builtin_amdgcn_s_waitcnt(0);
;         const unsigned x = xb_xcc_id();
;         unsigned nloc = st[0], nx = st[1];
;         if (nloc == 0u) { xcd_barrier_complete(bar, x, nloc, nx); st[0] = nloc; st[1] = nx; }
;         const unsigned old = xb_add(&bar[XB_XSUB(x)], 1u);
;         const unsigned gen = old / nloc;
;         if (old + 1u == (gen + 1u) * nloc) {
;             __builtin_amdgcn_fence(__ATOMIC_RELEASE, "agent");
;             asm volatile("s_waitcnt vmcnt(0)" ::: "memory");
;             const unsigned og = xb_add(&bar[XB_TOP], 1u);
;             const unsigned tg = og / nx;
;             if (og + 1u == (tg + 1u) * nx) xb_add(&bar[XB_TOPGEN], 1u);
.LBB0_1495:
	s_mov_b64 s[4:5], s[86:87]
	s_waitcnt vmcnt(0)
	s_waitcnt lgkmcnt(0)
	s_barrier
	s_and_saveexec_b64 s[6:7], s[88:89]
	s_cbranch_execz .LBB0_321
	v_readlane_b32 s0, v255, 22
	s_load_dwordx2 s[8:9], s[4:5], 0x98
	v_readlane_b32 s1, v255, 23
	s_getreg_b32 s10, hwreg(HW_REG_XCC_ID, 0, 4)
	v_mov_b32_e32 v0, s0
	v_mov_b32_e32 v1, s1
	ds_read_b32 v2, v0
	ds_read_b32 v3, v1
	s_and_b32 s10, s10, 15
	s_lshl_b32 s10, s10, 8
	v_mov_b32_e32 v0, 0x1400
	v_mov_b32_e32 v1, 1
	s_waitcnt vmcnt(0) lgkmcnt(0)
	s_add_u32 s10, s8, s10
	s_addc_u32 s11, s9, 0
	global_atomic_add v4, v0, v1, s[10:11] sc0
	v_cvt_f32_u32_e32 v5, v2
	v_mov_b32_e32 v0, 0x3400
	v_rcp_f32_e32 v5, v5
	s_waitcnt vmcnt(0)
	v_cvt_f32_u32_e32 v6, v4
	v_add_u32_e32 v4, 1, v4
	v_add_f32_e32 v6, 0.5, v6
	v_mul_f32_e32 v6, v6, v5
	v_cvt_u32_f32_e32 v6, v6
	v_add_u32_e32 v6, 1, v6
	v_mul_lo_u32 v7, v6, v2
	v_mul_lo_u32 v6, v6, v3
	v_cmp_eq_u32_e32 vcc, v4, v7
	s_cbranch_vccz .Lxb_poll_9
	buffer_wbl2 sc1
	s_waitcnt vmcnt(0)
	global_atomic_add v0, v1, s[8:9]

; __device__ __forceinline__ unsigned xb_ld(unsigned* p)              { return __hip_atomic_load(p, __ATOMIC_RELAXED, __HIP_MEMORY_SCOPE_AGENT); }
; __device__ __forceinline__ unsigned xb_add(unsigned* p, unsigned v) { return __hip_atomic_fetch_add(p, v, __ATOMIC_RELAXED, __HIP_MEMORY_SCOPE_AGENT); }
; #define XB_SPIN(cond, bar) do { unsigned _sp = 0; while (cond) { __builtin_amdgcn_s_sleep(1); \
;     if ((++_sp & 255u) == 0u) { if (xb_ld(&(bar)[XB_TMO])) break; if (_sp > XB_SPIN_CAP) { atomicAdd(&(bar)[XB_TMO], 1u); break; } } } } while (0)
; __device__ __forceinline__ void xcd_barrier(unsigned* bar, volatile LAS unsigned* st) {
;     ...
;             else XB_SPIN(xb_ld(&bar[XB_TOPGEN]) == tg, bar);
;             __builtin_amdgcn_fence(__ATOMIC_ACQUIRE, "agent");
;             xb_add(&bar[XB_XGEN(x)], 1u);
;             asm volatile("s_waitcnt vmcnt(0)" ::: "memory");
;         } else {
;             XB_SPIN(xb_ld(&bar[XB_XGEN(x)]) == gen, bar);
;             __builtin_amdgcn_fence(__ATOMIC_ACQUIRE, "agent");
;             asm volatile("s_waitcnt vmcnt(0)" ::: "memory");
;         }
;     }
;     __syncthreads();
; }
.Lxb_done_9:
	buffer_inv sc1
	s_waitcnt vmcnt(0)
	s_branch .LBB0_321
